# P5: workgroups that own only 5 tiles start about 14 us late so their epilogue store bursts interleave with the 6-tile workgroups' K-loops
# speedup vs baseline: 1.0178x; 1.0024x over previous
; #define LAS __attribute__((address_space(3)))
;     __host__ __device__ bool next(int i, Unit& u) const {
;         const long L = (long)i * G + c; if (L >= nwg) return false;
;         int wgid = (int)L; { const int q = nwg / NXCD, r = nwg % NXCD, xcd = wgid % NXCD, off = wgid / NXCD; wgid = (xcd < r ? xcd * (q + 1) : r * (q + 1) + (xcd - r) * q) + off; }
;         const int nig = WGM * nN, gid = wgid / nig, fm = gid * WGM, gsz = (nM - fm) < WGM ? (nM - fm) : WGM;
; __global__ void __launch_bounds__(512, 2) hymba_mega(Params p_arg) {
;     ...
;     {
;         const Params p = load_params();
;         pg8::Gemm g{(const bf16_t*)(p.ws + WS_H), (const bf16_t*)(p.ws + WS_WUP), 65 * 256, 2 * DFF, 1024};
;         UpOrder S; S.init(65 * 256, 2 * DFF, G, bx); S.tail_off = (long)WS_TAIL - (long)WS_H;
;         EpiUpF E{(const float*)(p.ws + WS_ROWSS), (const float*)(p.ws + WS_BIAS2), p.fcw, (bf16_t*)(p.ws + WS_ACT), (LAS float*)(lds + XCH_OFF)};
;         pg8::gemm_phase<EpiUpF, UpOrder, true, true>(lds, g, S, E);
.Lgb5_done:
.LBB0_549:
	s_or_b64 exec, exec, s[8:9]
	s_waitcnt lgkmcnt(0)
	s_barrier
	s_load_dwordx2 s[4:5], s[96:97], 0
	s_load_dwordx2 s[6:7], s[96:97], 8
	s_load_dwordx2 s[10:11], s[96:97], 16
	s_load_dwordx2 s[12:13], s[96:97], 24
	s_load_dwordx2 s[14:15], s[96:97], 32
	s_load_dwordx2 s[16:17], s[96:97], 40
	s_load_dwordx2 s[18:19], s[96:97], 48
	s_load_dwordx2 s[20:21], s[96:97], 56
	s_load_dwordx2 s[22:23], s[96:97], 64
	s_load_dwordx2 s[28:29], s[96:97], 72
	s_load_dwordx2 s[34:35], s[96:97], 80
	s_load_dwordx2 s[36:37], s[96:97], 88
	s_load_dwordx2 s[38:39], s[96:97], 96
	s_load_dwordx2 s[30:31], s[96:97], 104
	s_load_dwordx2 s[40:41], s[96:97], 112
	s_load_dwordx2 s[42:43], s[96:97], 120
	s_load_dwordx2 s[8:9], s[96:97], 128
	s_waitcnt lgkmcnt(0)
	s_cmp_lt_u32 s2, 150
	s_cbranch_scc1 .Lp5_nodelay
	s_sleep 127
	s_sleep 127
	s_sleep 127
	s_sleep 127
.Lp5_nodelay:
	v_mov_b32_e32 v9, v208
	s_cmpk_lt_i32 s2, 0x596
	v_and_b32_e32 v8, 0x1ff, v9
	s_cselect_b64 s[10:11], -1, 0
	s_cmpk_gt_i32 s2, 0x595
	v_readfirstlane_b32 s4, v8
	s_cbranch_scc1 .LBB0_555
	s_ashr_i32 s0, s2, 31
	s_lshr_b32 s0, s0, 29
	s_add_i32 s3, s2, s0
	s_and_b32 s0, s3, -8
	s_sub_i32 s5, s2, s0
	s_cmp_gt_i32 s5, 5
	s_cbranch_scc0 .LBB0_552
	s_mul_i32 s0, s5, 0xb2
	s_add_i32 s6, s0, 6
	s_cbranch_execz .LBB0_553
	s_branch .LBB0_554
